# bprep: all 10 head loads hoisted to the top of each token iteration (one wait); FFN-up GEMM: accumulator zeroing replaced by a peeled first half-iteration whose first-touch MFMAs take C=0
# speedup vs baseline: 1.0367x; 1.0019x over previous
; DI float bflo(unsigned u) { return __uint_as_float(u << 16); }
; DI float bfhi(unsigned u) { return __uint_as_float(u & 0xffff0000u); }
; DI unsigned pack2(float lo, float hi) { f32x2_t v = {lo, hi}; return __builtin_bit_cast(unsigned, __builtin_convertvector(v, bf16x2_t)); }
; DI void bprep_phase(const Params& p) {
;     ...
;   for (int t = blockIdx.x * 16 + tl; t < NTOK; t += gridDim.x * 16) {
;     const int pos = (t < PROMPT_T) ? t : ((t - PROMPT_T) & (SAMPLE_T - 1));
;     const float ang = (float)((pi < 16) ? (pos >> 6) : (pos & 63)) * fr;
;     const float cs = __cosf(ang), sn = __sinf(ang);
;     unsigned* rowp = (unsigned*)(p.big + (size_t)t * 2304);
; #pragma unroll
;     for (int hd = 0; hd < 10; ++hd) {
;       const int col = (hd < 8) ? (1536 + hd * 64) : (2048 + (hd - 8) * 64);
;       unsigned u = rowp[(col >> 1) + pi];
;       float x1 = bflo(u), x2 = bfhi(u);
;       float ss = x1 * x1 + x2 * x2;
; #pragma unroll
;       for (int o = 16; o > 0; o >>= 1) ss += __shfl_xor(ss, o);
;       const float r = rsqrtf(ss * (1.0f / 64.0f) + EPS);
;       x1 = x1 * r * ((hd < 8) ? qg0 : kg0); x2 = x2 * r * ((hd < 8) ? qg1 : kg1);
;       const float qs = (hd < 8) ? 0.125f * LOG2E : 1.f;
;       rowp[(col >> 1) + pi] = pack2((x1 * cs - x2 * sn) * qs, (x1 * sn + x2 * cs) * qs);
;     }
.LBB0_249:
	s_movk_i32 s0, 0x4000
	v_cmp_gt_i32_e64 s[0:1], s0, v9
	v_and_b32_e32 v0, 0xfff, v9
	s_nop 0
	v_cndmask_b32_e64 v0, v0, v9, s[0:1]
	v_mad_i64_i32 v[10:11], s[0:1], v9, s24, v[6:7]
	global_load_dword v30, v[10:11], off offset:3072
	global_load_dword v31, v[10:11], off offset:3200
	s_movk_i32 s0, 0x1000
	v_add_co_u32_e64 v40, s[0:1], s0, v10
	s_nop 1
	v_addc_co_u32_e64 v41, s[0:1], 0, v11, s[0:1]
	global_load_dword v32, v[10:11], off offset:3456
	global_load_dword v33, v[10:11], off offset:3328
	global_load_dword v34, v[10:11], off offset:3712
	global_load_dword v35, v[10:11], off offset:3584
	global_load_dword v36, v[10:11], off offset:3968
	global_load_dword v37, v[10:11], off offset:3840
	global_load_dword v38, v[40:41], off
	global_load_dword v39, v[40:41], off offset:128
	s_mov_b32 s0, 0x358637bd
	v_ashrrev_i32_e32 v8, 6, v0
	v_and_b32_e32 v0, 63, v0
	v_cndmask_b32_e32 v0, v0, v8, vcc
	v_cvt_f32_i32_e32 v0, v0
	v_mul_f32_e32 v0, v14, v0
	v_mul_f32_e32 v8, 0.15915494, v0
	v_cos_f32_e32 v0, v8
	v_sin_f32_e32 v8, v8
	s_waitcnt vmcnt(0)
	v_lshlrev_b32_e32 v20, 16, v30
	v_and_b32_e32 v21, 0xffff0000, v30
	v_lshlrev_b32_e32 v22, 16, v31
	v_and_b32_e32 v23, 0xffff0000, v31
	v_pk_mul_f32 v[12:13], v[20:21], v[20:21]
	v_pk_mul_f32 v[24:25], v[22:23], v[22:23]
	v_mov_b32_e32 v27, v12
	v_mov_b32_e32 v26, v24
	v_mov_b32_e32 v12, v25
	v_pk_add_f32 v[12:13], v[26:27], v[12:13]
	ds_bpermute_b32 v25, v15, v13
	ds_bpermute_b32 v24, v15, v12
	s_waitcnt lgkmcnt(0)
	v_pk_add_f32 v[12:13], v[12:13], v[24:25]
	ds_bpermute_b32 v25, v16, v13
	ds_bpermute_b32 v24, v16, v12
	s_waitcnt lgkmcnt(0)
	v_pk_add_f32 v[12:13], v[12:13], v[24:25]
	ds_bpermute_b32 v25, v17, v13
	ds_bpermute_b32 v24, v17, v12
	s_waitcnt lgkmcnt(0)
	v_pk_add_f32 v[12:13], v[12:13], v[24:25]
	ds_bpermute_b32 v25, v18, v13
	ds_bpermute_b32 v24, v18, v12
	s_waitcnt lgkmcnt(0)
	v_pk_add_f32 v[12:13], v[12:13], v[24:25]
	ds_bpermute_b32 v25, v19, v13
	ds_bpermute_b32 v24, v19, v12
	s_waitcnt lgkmcnt(0)
	v_pk_add_f32 v[24:25], v[12:13], v[24:25]
	v_mov_b64_e32 v[12:13], s[0:1]
	v_pk_fma_f32 v[24:25], v[24:25], s[8:9], v[12:13] op_sel_hi:[1,0,0]
	s_nop 0
	v_mul_f32_e32 v26, 0x4b800000, v25
	v_cmp_gt_f32_e64 s[38:39], s4, v25
	v_cmp_gt_f32_e64 s[0:1], s4, v24
	s_nop 0
	v_cndmask_b32_e64 v25, v25, v26, s[38:39]
	v_rsq_f32_e32 v25, v25
	s_nop 0
	v_mul_f32_e32 v26, 0x45800000, v25
	v_cndmask_b32_e64 v26, v25, v26, s[38:39]
	v_pk_mul_f32 v[20:21], v[26:27], v[20:21] op_sel_hi:[0,1]
	v_pk_mul_f32 v[20:21], v[2:3], v[20:21]
	s_nop 0
	v_pk_mul_f32 v[26:27], v[8:9], v[20:21] op_sel_hi:[0,1]
	v_pk_fma_f32 v[28:29], v[0:1], v[20:21], v[26:27] op_sel:[0,0,1] op_sel_hi:[1,1,0] neg_lo:[0,0,1] neg_hi:[0,0,1]
	v_pk_fma_f32 v[20:21], v[0:1], v[20:21], v[26:27] op_sel:[0,0,1] op_sel_hi:[0,1,0]
	v_mov_b32_e32 v29, v21
	v_pk_mul_f32 v[20:21], v[28:29], s[6:7] op_sel_hi:[1,0]
	s_nop 0
	v_cvt_pk_bf16_f32 v20, v20, v21
	global_store_dword v[10:11], v20, off offset:3072
	v_mul_f32_e32 v20, 0x4b800000, v24
	v_cndmask_b32_e64 v20, v24, v20, s[0:1]
	v_rsq_f32_e32 v20, v20
	s_nop 0
	v_mul_f32_e32 v21, 0x45800000, v20
	v_cndmask_b32_e64 v20, v20, v21, s[0:1]
	v_pk_mul_f32 v[20:21], v[20:21], v[22:23] op_sel_hi:[0,1]
	v_pk_mul_f32 v[20:21], v[2:3], v[20:21]
	s_nop 0
	v_pk_mul_f32 v[22:23], v[8:9], v[20:21] op_sel_hi:[0,1]
	v_pk_fma_f32 v[24:25], v[0:1], v[20:21], v[22:23] op_sel:[0,0,1] op_sel_hi:[1,1,0] neg_lo:[0,0,1] neg_hi:[0,0,1]
	v_pk_fma_f32 v[20:21], v[0:1], v[20:21], v[22:23] op_sel:[0,0,1] op_sel_hi:[0,1,0]
	v_mov_b32_e32 v25, v21
	v_pk_mul_f32 v[20:21], v[24:25], s[6:7] op_sel_hi:[1,0]
	v_cvt_pk_bf16_f32 v20, v20, v21
	v_lshlrev_b32_e32 v24, 16, v32
	global_store_dword v[10:11], v20, off offset:3200
	v_lshlrev_b32_e32 v20, 16, v33
	v_and_b32_e32 v21, 0xffff0000, v33
	v_and_b32_e32 v25, 0xffff0000, v32
	v_pk_mul_f32 v[22:23], v[20:21], v[20:21]
	v_pk_mul_f32 v[26:27], v[24:25], v[24:25]
	v_mov_b32_e32 v29, v22
	v_mov_b32_e32 v28, v26
	v_mov_b32_e32 v22, v27
	v_pk_add_f32 v[22:23], v[28:29], v[22:23]
	ds_bpermute_b32 v27, v15, v23
	ds_bpermute_b32 v26, v15, v22
	s_waitcnt lgkmcnt(0)
	v_pk_add_f32 v[22:23], v[22:23], v[26:27]
	ds_bpermute_b32 v27, v16, v23
	ds_bpermute_b32 v26, v16, v22
	s_waitcnt lgkmcnt(0)
	v_pk_add_f32 v[22:23], v[22:23], v[26:27]
	ds_bpermute_b32 v27, v17, v23
	ds_bpermute_b32 v26, v17, v22
	s_waitcnt lgkmcnt(0)
	v_pk_add_f32 v[22:23], v[22:23], v[26:27]
	ds_bpermute_b32 v27, v18, v23
	ds_bpermute_b32 v26, v18, v22
	s_waitcnt lgkmcnt(0)
	v_pk_add_f32 v[22:23], v[22:23], v[26:27]
	ds_bpermute_b32 v27, v19, v23
	ds_bpermute_b32 v26, v19, v22
	s_waitcnt lgkmcnt(0)
	v_pk_add_f32 v[22:23], v[22:23], v[26:27]
	s_nop 0
	v_pk_fma_f32 v[22:23], v[22:23], s[8:9], v[12:13] op_sel_hi:[1,0,0]
	s_nop 0
	v_mul_f32_e32 v26, 0x4b800000, v23
	v_cmp_gt_f32_e64 s[38:39], s4, v23
	v_cmp_gt_f32_e64 s[0:1], s4, v22
	s_nop 0
	v_cndmask_b32_e64 v23, v23, v26, s[38:39]
	v_rsq_f32_e32 v23, v23
	s_nop 0
	v_mul_f32_e32 v26, 0x45800000, v23
	v_cndmask_b32_e64 v26, v23, v26, s[38:39]
	v_pk_mul_f32 v[20:21], v[26:27], v[20:21] op_sel_hi:[0,1]
	v_pk_mul_f32 v[20:21], v[2:3], v[20:21]
	s_nop 0
	v_pk_mul_f32 v[26:27], v[8:9], v[20:21] op_sel_hi:[0,1]
	v_pk_fma_f32 v[28:29], v[0:1], v[20:21], v[26:27] op_sel:[0,0,1] op_sel_hi:[1,1,0] neg_lo:[0,0,1] neg_hi:[0,0,1]
	v_pk_fma_f32 v[20:21], v[0:1], v[20:21], v[26:27] op_sel:[0,0,1] op_sel_hi:[0,1,0]
	v_mov_b32_e32 v29, v21
	v_pk_mul_f32 v[20:21], v[28:29], s[6:7] op_sel_hi:[1,0]
	s_nop 0
	v_cvt_pk_bf16_f32 v20, v20, v21
	global_store_dword v[10:11], v20, off offset:3328
	v_mul_f32_e32 v20, 0x4b800000, v22
	v_cndmask_b32_e64 v20, v22, v20, s[0:1]
	v_rsq_f32_e32 v20, v20
	s_nop 0
	v_mul_f32_e32 v21, 0x45800000, v20
	v_cndmask_b32_e64 v20, v20, v21, s[0:1]
	v_pk_mul_f32 v[20:21], v[20:21], v[24:25] op_sel_hi:[0,1]
	v_pk_mul_f32 v[20:21], v[2:3], v[20:21]
	s_nop 0
	v_pk_mul_f32 v[22:23], v[8:9], v[20:21] op_sel_hi:[0,1]
	v_pk_fma_f32 v[24:25], v[0:1], v[20:21], v[22:23] op_sel:[0,0,1] op_sel_hi:[1,1,0] neg_lo:[0,0,1] neg_hi:[0,0,1]
	v_pk_fma_f32 v[20:21], v[0:1], v[20:21], v[22:23] op_sel:[0,0,1] op_sel_hi:[0,1,0]
	v_mov_b32_e32 v25, v21
	v_pk_mul_f32 v[20:21], v[24:25], s[6:7] op_sel_hi:[1,0]
	v_cvt_pk_bf16_f32 v20, v20, v21
	v_lshlrev_b32_e32 v24, 16, v34
	global_store_dword v[10:11], v20, off offset:3456
	v_lshlrev_b32_e32 v20, 16, v35
	v_and_b32_e32 v21, 0xffff0000, v35
	v_and_b32_e32 v25, 0xffff0000, v34
	v_pk_mul_f32 v[22:23], v[20:21], v[20:21]
	v_pk_mul_f32 v[26:27], v[24:25], v[24:25]
	v_mov_b32_e32 v29, v22
	v_mov_b32_e32 v28, v26
	v_mov_b32_e32 v22, v27
	v_pk_add_f32 v[22:23], v[28:29], v[22:23]
	ds_bpermute_b32 v27, v15, v23
	ds_bpermute_b32 v26, v15, v22
	s_waitcnt lgkmcnt(0)
; DI float bflo(unsigned u) { return __uint_as_float(u << 16); }
; DI float bfhi(unsigned u) { return __uint_as_float(u & 0xffff0000u); }
; DI unsigned pack2(float lo, float hi) { f32x2_t v = {lo, hi}; return __builtin_bit_cast(unsigned, __builtin_convertvector(v, bf16x2_t)); }
; DI void bprep_phase(const Params& p) {
;     ...
;     for (int hd = 0; hd < 10; ++hd) {
;       const int col = (hd < 8) ? (1536 + hd * 64) : (2048 + (hd - 8) * 64);
;       unsigned u = rowp[(col >> 1) + pi];
;       float x1 = bflo(u), x2 = bfhi(u);
;       float ss = x1 * x1 + x2 * x2;
; #pragma unroll
;       for (int o = 16; o > 0; o >>= 1) ss += __shfl_xor(ss, o);
;       const float r = rsqrtf(ss * (1.0f / 64.0f) + EPS);
;       x1 = x1 * r * ((hd < 8) ? qg0 : kg0); x2 = x2 * r * ((hd < 8) ? qg1 : kg1);
;       const float qs = (hd < 8) ? 0.125f * LOG2E : 1.f;
;       rowp[(col >> 1) + pi] = pack2((x1 * cs - x2 * sn) * qs, (x1 * sn + x2 * cs) * qs);
;     }
	v_pk_add_f32 v[22:23], v[22:23], v[26:27]
	ds_bpermute_b32 v27, v16, v23
	ds_bpermute_b32 v26, v16, v22
	s_waitcnt lgkmcnt(0)
	v_pk_add_f32 v[22:23], v[22:23], v[26:27]
	ds_bpermute_b32 v27, v17, v23
	ds_bpermute_b32 v26, v17, v22
	s_waitcnt lgkmcnt(0)
	v_pk_add_f32 v[22:23], v[22:23], v[26:27]
	ds_bpermute_b32 v27, v18, v23
	ds_bpermute_b32 v26, v18, v22
	s_waitcnt lgkmcnt(0)
	v_pk_add_f32 v[22:23], v[22:23], v[26:27]
	ds_bpermute_b32 v27, v19, v23
	ds_bpermute_b32 v26, v19, v22
	s_waitcnt lgkmcnt(0)
	v_pk_add_f32 v[22:23], v[22:23], v[26:27]
	s_nop 0
	v_pk_fma_f32 v[22:23], v[22:23], s[8:9], v[12:13] op_sel_hi:[1,0,0]
	s_nop 0
	v_mul_f32_e32 v26, 0x4b800000, v23
	v_cmp_gt_f32_e64 s[38:39], s4, v23
	v_cmp_gt_f32_e64 s[0:1], s4, v22
	s_nop 0
	v_cndmask_b32_e64 v23, v23, v26, s[38:39]
	v_rsq_f32_e32 v23, v23
	s_nop 0
	v_mul_f32_e32 v26, 0x45800000, v23
	v_cndmask_b32_e64 v26, v23, v26, s[38:39]
	v_pk_mul_f32 v[20:21], v[26:27], v[20:21] op_sel_hi:[0,1]
	v_pk_mul_f32 v[20:21], v[2:3], v[20:21]
	s_nop 0
	v_pk_mul_f32 v[26:27], v[8:9], v[20:21] op_sel_hi:[0,1]
	v_pk_fma_f32 v[28:29], v[0:1], v[20:21], v[26:27] op_sel:[0,0,1] op_sel_hi:[1,1,0] neg_lo:[0,0,1] neg_hi:[0,0,1]
	v_pk_fma_f32 v[20:21], v[0:1], v[20:21], v[26:27] op_sel:[0,0,1] op_sel_hi:[0,1,0]
	v_mov_b32_e32 v29, v21
	v_pk_mul_f32 v[20:21], v[28:29], s[6:7] op_sel_hi:[1,0]
	s_nop 0
	v_cvt_pk_bf16_f32 v20, v20, v21
	global_store_dword v[10:11], v20, off offset:3584
	v_mul_f32_e32 v20, 0x4b800000, v22
	v_cndmask_b32_e64 v20, v22, v20, s[0:1]
	v_rsq_f32_e32 v20, v20
	s_nop 0
	v_mul_f32_e32 v21, 0x45800000, v20
	v_cndmask_b32_e64 v20, v20, v21, s[0:1]
	v_pk_mul_f32 v[20:21], v[20:21], v[24:25] op_sel_hi:[0,1]
	v_pk_mul_f32 v[20:21], v[2:3], v[20:21]
	s_nop 0
	v_pk_mul_f32 v[22:23], v[8:9], v[20:21] op_sel_hi:[0,1]
	v_pk_fma_f32 v[24:25], v[0:1], v[20:21], v[22:23] op_sel:[0,0,1] op_sel_hi:[1,1,0] neg_lo:[0,0,1] neg_hi:[0,0,1]
	v_pk_fma_f32 v[20:21], v[0:1], v[20:21], v[22:23] op_sel:[0,0,1] op_sel_hi:[0,1,0]
	v_mov_b32_e32 v25, v21
	v_pk_mul_f32 v[20:21], v[24:25], s[6:7] op_sel_hi:[1,0]
	v_cvt_pk_bf16_f32 v20, v20, v21
	v_lshlrev_b32_e32 v24, 16, v36
	global_store_dword v[10:11], v20, off offset:3712
	v_lshlrev_b32_e32 v20, 16, v37
	v_and_b32_e32 v21, 0xffff0000, v37
	v_and_b32_e32 v25, 0xffff0000, v36
	v_pk_mul_f32 v[22:23], v[20:21], v[20:21]
	v_pk_mul_f32 v[26:27], v[24:25], v[24:25]
	v_mov_b32_e32 v29, v22
	v_mov_b32_e32 v28, v26
	v_mov_b32_e32 v22, v27
	v_pk_add_f32 v[22:23], v[28:29], v[22:23]
	ds_bpermute_b32 v27, v15, v23
	ds_bpermute_b32 v26, v15, v22
	s_waitcnt lgkmcnt(0)
	v_pk_add_f32 v[22:23], v[22:23], v[26:27]
	ds_bpermute_b32 v27, v16, v23
	ds_bpermute_b32 v26, v16, v22
	s_waitcnt lgkmcnt(0)
	v_pk_add_f32 v[22:23], v[22:23], v[26:27]
	ds_bpermute_b32 v27, v17, v23
	ds_bpermute_b32 v26, v17, v22
	s_waitcnt lgkmcnt(0)
	v_pk_add_f32 v[22:23], v[22:23], v[26:27]
	ds_bpermute_b32 v27, v18, v23
	ds_bpermute_b32 v26, v18, v22
	s_waitcnt lgkmcnt(0)
	v_pk_add_f32 v[22:23], v[22:23], v[26:27]
	ds_bpermute_b32 v27, v19, v23
	ds_bpermute_b32 v26, v19, v22
	s_waitcnt lgkmcnt(0)
; DI float bflo(unsigned u) { return __uint_as_float(u << 16); }
; DI float bfhi(unsigned u) { return __uint_as_float(u & 0xffff0000u); }
; DI unsigned pack2(float lo, float hi) { f32x2_t v = {lo, hi}; return __builtin_bit_cast(unsigned, __builtin_convertvector(v, bf16x2_t)); }
; DI void bprep_phase(const Params& p) {
;     ...
;     for (int hd = 0; hd < 10; ++hd) {
;       const int col = (hd < 8) ? (1536 + hd * 64) : (2048 + (hd - 8) * 64);
;       unsigned u = rowp[(col >> 1) + pi];
;       float x1 = bflo(u), x2 = bfhi(u);
;       float ss = x1 * x1 + x2 * x2;
; #pragma unroll
;       for (int o = 16; o > 0; o >>= 1) ss += __shfl_xor(ss, o);
;       const float r = rsqrtf(ss * (1.0f / 64.0f) + EPS);
;       x1 = x1 * r * ((hd < 8) ? qg0 : kg0); x2 = x2 * r * ((hd < 8) ? qg1 : kg1);
;       const float qs = (hd < 8) ? 0.125f * LOG2E : 1.f;
;       rowp[(col >> 1) + pi] = pack2((x1 * cs - x2 * sn) * qs, (x1 * sn + x2 * cs) * qs);
;     }
;   }
; }
; template <int MODE>
; DI void naive_attn(const Params& p, const bf16_t* __restrict__ proj, int ld, int qoff, int koff, int voff, int nqh, int G, bf16_t* cat, int cat_off) {
	v_pk_add_f32 v[22:23], v[22:23], v[26:27]
	s_nop 0
	v_pk_fma_f32 v[22:23], v[22:23], s[8:9], v[12:13] op_sel_hi:[1,0,0]
	s_nop 0
	v_mul_f32_e32 v26, 0x4b800000, v23
	v_cmp_gt_f32_e64 s[38:39], s4, v23
	v_cmp_gt_f32_e64 s[0:1], s4, v22
	s_nop 0
	v_cndmask_b32_e64 v23, v23, v26, s[38:39]
	v_rsq_f32_e32 v23, v23
	s_nop 0
	v_mul_f32_e32 v26, 0x45800000, v23
	v_cndmask_b32_e64 v26, v23, v26, s[38:39]
	v_pk_mul_f32 v[20:21], v[26:27], v[20:21] op_sel_hi:[0,1]
	v_pk_mul_f32 v[20:21], v[2:3], v[20:21]
	s_nop 0
	v_pk_mul_f32 v[26:27], v[8:9], v[20:21] op_sel_hi:[0,1]
	v_pk_fma_f32 v[28:29], v[0:1], v[20:21], v[26:27] op_sel:[0,0,1] op_sel_hi:[1,1,0] neg_lo:[0,0,1] neg_hi:[0,0,1]
	v_pk_fma_f32 v[20:21], v[0:1], v[20:21], v[26:27] op_sel:[0,0,1] op_sel_hi:[0,1,0]
	v_mov_b32_e32 v29, v21
	v_pk_mul_f32 v[20:21], v[28:29], s[6:7] op_sel_hi:[1,0]
	s_nop 0
	v_cvt_pk_bf16_f32 v20, v20, v21
	global_store_dword v[10:11], v20, off offset:3840
	v_mul_f32_e32 v20, 0x4b800000, v22
	v_cndmask_b32_e64 v20, v22, v20, s[0:1]
	v_rsq_f32_e32 v20, v20
	s_nop 0
	v_mul_f32_e32 v21, 0x45800000, v20
	v_cndmask_b32_e64 v20, v20, v21, s[0:1]
	v_pk_mul_f32 v[20:21], v[20:21], v[24:25] op_sel_hi:[0,1]
	v_pk_mul_f32 v[20:21], v[2:3], v[20:21]
	s_movk_i32 s0, 0x1000
	v_pk_mul_f32 v[22:23], v[8:9], v[20:21] op_sel_hi:[0,1]
	v_pk_fma_f32 v[24:25], v[0:1], v[20:21], v[22:23] op_sel:[0,0,1] op_sel_hi:[1,1,0] neg_lo:[0,0,1] neg_hi:[0,0,1]
	v_pk_fma_f32 v[20:21], v[0:1], v[20:21], v[22:23] op_sel:[0,0,1] op_sel_hi:[0,1,0]
	v_mov_b32_e32 v25, v21
	v_pk_mul_f32 v[20:21], v[24:25], s[6:7] op_sel_hi:[1,0]
	s_nop 0
	v_cvt_pk_bf16_f32 v20, v20, v21
	global_store_dword v[10:11], v20, off offset:3968
	v_add_co_u32_e64 v10, s[0:1], s0, v10
	s_nop 1
	v_addc_co_u32_e64 v11, s[0:1], 0, v11, s[0:1]
	v_lshlrev_b32_e32 v20, 16, v38
	v_and_b32_e32 v21, 0xffff0000, v38
	v_lshlrev_b32_e32 v24, 16, v39
	v_and_b32_e32 v25, 0xffff0000, v39
	v_pk_mul_f32 v[22:23], v[20:21], v[20:21]
	v_pk_mul_f32 v[26:27], v[24:25], v[24:25]
	v_mov_b32_e32 v29, v22
	v_mov_b32_e32 v28, v26
	v_mov_b32_e32 v22, v27
	v_pk_add_f32 v[22:23], v[28:29], v[22:23]
	ds_bpermute_b32 v27, v15, v23
	ds_bpermute_b32 v26, v15, v22
	s_waitcnt lgkmcnt(0)
	v_pk_add_f32 v[22:23], v[22:23], v[26:27]
	ds_bpermute_b32 v27, v16, v23
	ds_bpermute_b32 v26, v16, v22
	s_waitcnt lgkmcnt(0)
	v_pk_add_f32 v[22:23], v[22:23], v[26:27]
	ds_bpermute_b32 v27, v17, v23
	ds_bpermute_b32 v26, v17, v22
	s_waitcnt lgkmcnt(0)
	v_pk_add_f32 v[22:23], v[22:23], v[26:27]
	ds_bpermute_b32 v27, v18, v23
	ds_bpermute_b32 v26, v18, v22
	s_waitcnt lgkmcnt(0)
	v_pk_add_f32 v[22:23], v[22:23], v[26:27]
	ds_bpermute_b32 v27, v19, v23
	ds_bpermute_b32 v26, v19, v22
	s_waitcnt lgkmcnt(0)
	v_pk_add_f32 v[22:23], v[22:23], v[26:27]
	s_nop 0
	v_pk_fma_f32 v[12:13], v[22:23], s[8:9], v[12:13] op_sel_hi:[1,0,0]
	s_nop 0
	v_mul_f32_e32 v22, 0x4b800000, v13
	v_cmp_gt_f32_e64 s[38:39], s4, v13
	v_cmp_gt_f32_e64 s[0:1], s4, v12
	s_nop 0
	v_cndmask_b32_e64 v13, v13, v22, s[38:39]
	v_rsq_f32_e32 v13, v13
	s_nop 0
	v_mul_f32_e32 v22, 0x45800000, v13
	v_cndmask_b32_e64 v22, v13, v22, s[38:39]
	v_pk_mul_f32 v[20:21], v[22:23], v[20:21] op_sel_hi:[0,1]
	v_pk_mul_f32 v[20:21], v[4:5], v[20:21]
	s_nop 0
	v_pk_mul_f32 v[22:23], v[8:9], v[20:21] op_sel_hi:[0,1]
	v_pk_fma_f32 v[26:27], v[0:1], v[20:21], v[22:23] op_sel:[0,0,1] op_sel_hi:[1,1,0] neg_lo:[0,0,1] neg_hi:[0,0,1]
	v_pk_fma_f32 v[20:21], v[0:1], v[20:21], v[22:23] op_sel:[0,0,1] op_sel_hi:[0,1,0]
	v_cvt_pk_bf16_f32 v13, v26, v21
	global_store_dword v[10:11], v13, off
	v_mul_f32_e32 v13, 0x4b800000, v12
	v_cndmask_b32_e64 v12, v12, v13, s[0:1]
	v_rsq_f32_e32 v12, v12
	s_nop 0
	v_mul_f32_e32 v13, 0x45800000, v12
	v_cndmask_b32_e64 v12, v12, v13, s[0:1]
	v_pk_mul_f32 v[12:13], v[12:13], v[24:25] op_sel_hi:[0,1]
	v_pk_mul_f32 v[12:13], v[4:5], v[12:13]
	s_nop 0
	v_pk_mul_f32 v[20:21], v[8:9], v[12:13] op_sel_hi:[0,1]
	v_add_u32_e32 v9, s17, v9
	v_pk_fma_f32 v[22:23], v[0:1], v[12:13], v[20:21] op_sel:[0,0,1] op_sel_hi:[1,1,0] neg_lo:[0,0,1] neg_hi:[0,0,1]
	v_pk_fma_f32 v[12:13], v[0:1], v[12:13], v[20:21] op_sel:[0,0,1] op_sel_hi:[0,1,0]
	v_cmp_lt_i32_e64 s[0:1], s63, v9
	v_cvt_pk_bf16_f32 v0, v22, v13
	s_or_b64 s[40:41], s[0:1], s[40:41]
	global_store_dword v[10:11], v0, off offset:128
	s_andn2_b64 exec, exec, s[40:41]
	s_cbranch_execnz .LBB0_249

;   DI void init(f32x4 (&acc)[2][2][4][2], const Unit&, int, int, int, int) const { acc_zero(acc); }
;   DI void init(f32x4 (&acc)[2][2][4][2], const Unit&, int, int, int, int) const { acc_zero(acc); }
; #define PG8_STAGE(bufoff, gbase, voff) do { _Pragma("unroll") for (int _i = 0; _i < 2; ++_i) \
;     __builtin_amdgcn_global_load_lds((const unsigned*)((const char*)(gbase) + (voff)[_i]), (PG8_LAS unsigned*)(lds + (bufoff) + ldsw + _i * 8192), 16, 0, 0); } while (0)
; #define PG8_LDA(dst, b, h) do { _Pragma("unroll") for (int m = 0; m < 4; ++m) _Pragma("unroll") for (int k = 0; k < 2; ++k) dst[m][k] = *(const PG8_LAS bf16x8*)(lds + PG8_SA(b, h) + aoff + m * 2048 + k * 1024); } while (0)
; #define PG8_LDB(dst, b, h) do { _Pragma("unroll") for (int n = 0; n < 2; ++n) _Pragma("unroll") for (int k = 0; k < 2; ++k) dst[n][k] = *(const PG8_LAS bf16x8*)(lds + PG8_SB(b, h) + boff + n * 2048 + k * 1024); } while (0)
; #define PG8_MMA(ai, bj, At, Bt) do { __builtin_amdgcn_s_setprio(1); _Pragma("unroll") for (int m = 0; m < 4; ++m) _Pragma("unroll") for (int n = 0; n < 2; ++n) _Pragma("unroll") for (int k = 0; k < 2; ++k) \
;     acc[ai][bj][m][n] = __builtin_amdgcn_mfma_f32_16x16x32_bf16(Bt[n][k], At[m][k], acc[ai][bj][m][n], 0, 0, 0); __builtin_amdgcn_s_setprio(0); } while (0)
; #define PG8_WAIT_L(n) asm volatile("s_waitcnt lgkmcnt(" #n ")" ::: "memory")
; #define PG8_BAR __builtin_amdgcn_s_barrier()
; #define PG8_SCHED __builtin_amdgcn_sched_barrier(0)
; template <class Epi>
; DI void gemm_phase(const bf16_t* __restrict__ gA, const bf16_t* __restrict__ gBt, int M, int N, int K, const Epi& E, char* lds_generic) {
;     ...
;   f32x4 acc[2][2][4][2];
;   E.init(acc, cur, wr, wc, fr, fq);
;     ...
;     for (int t = 0; t < nt; t += 2) {
;       const bool last = (t == nt - 2);
;       const char* a1 = cA + (size_t)(t + 1) * kstep;
;       const char* a2 = last ? nA : cA + (size_t)(t + 2) * kstep; const char* b2 = last ? nB : cB + (size_t)(t + 2) * kstep;
;       const char* a3 = a2 + kstep; const char* b3 = b2 + kstep;
;       PG8_LDB(B0, 0, 0); PG8_SCHED; PG8_LDA(At, 0, 0); PG8_STAGE(PG8_SA(1, 1), a1 + hstep, voffA);
;       PG8_WAIT_L(8); PG8_BAR; PG8_WAIT_L(0); PG8_MMA(0, 0, At, B0); PG8_BAR; PG8_SCHED;
;       PG8_LDB(B1, 0, 1); PG8_STAGE(PG8_SB(0, 0), b2, voffB);
;       PG8_BAR; PG8_WAIT_L(0); PG8_MMA(0, 1, At, B1); PG8_BAR;
.LBB0_604:
	s_ashr_i32 s87, s86, 31
	s_lshl_b64 s[20:21], s[86:87], 19
	s_add_u32 s88, s82, s20
	s_addc_u32 s89, s83, s21
	s_and_b64 s[20:21], s[38:39], exec
	s_cselect_b32 s20, s89, s29
	s_cselect_b32 s21, s88, s28
	s_ashr_i32 s27, s26, 31
	s_lshl_b64 s[22:23], s[26:27], 19
	s_add_u32 s90, s16, s22
	s_addc_u32 s91, s4, s23
	s_and_b64 s[22:23], s[38:39], exec
	s_cselect_b32 s27, s91, s31
	s_cselect_b32 s42, s90, s30
	s_add_u32 vcc_lo, s28, 0x40080
	s_addc_u32 vcc_hi, s29, 0
	s_add_u32 s87, s30, 0x100
	s_addc_u32 s22, s31, 0
	s_mov_b32 s23, -2
	v_or_b32_e32 v50, 0x10000, v155
	v_add_u32_e32 v146, 0x10400, v155
	v_add_u32_e32 v158, 0x10800, v155
	ds_read_b128 v[50:53], v50
	ds_read_b128 v[146:149], v146
	v_add_u32_e32 v163, 0x10c00, v155
	ds_read_b128 v[158:161], v158
	ds_read_b128 v[166:169], v163
	s_add_u32 s24, vcc_lo, 0xfffc0080
	s_addc_u32 s25, vcc_hi, -1
	s_cmp_eq_u32 s23, 12
	s_cselect_b32 s31, s20, s25
	s_cselect_b32 s30, s21, s24
	s_cselect_b32 s29, s27, s22
	s_cselect_b32 s28, s42, s87
	v_lshl_add_u64 v[202:203], vcc, 0, v[142:143]
	s_add_i32 m0, s72, 0xc000
	ds_read_b128 v[170:173], v154
	ds_read_b128 v[174:177], v154 offset:1024
	ds_read_b128 v[178:181], v154 offset:2048
	ds_read_b128 v[182:185], v154 offset:3072
	ds_read_b128 v[186:189], v154 offset:4096
	ds_read_b128 v[190:193], v154 offset:5120
	ds_read_b128 v[194:197], v154 offset:6144
	ds_read_b128 v[198:201], v154 offset:7168
	global_load_lds_dwordx4 v[202:203], off
	v_lshl_add_u64 v[202:203], vcc, 0, v[144:145]
	s_add_i32 m0, s72, 0xe000
	s_nop 0
	global_load_lds_dwordx4 v[202:203], off
	s_waitcnt lgkmcnt(8)
	s_barrier
	s_waitcnt lgkmcnt(0)
	s_setprio 1
	s_waitcnt lgkmcnt(0)
	v_mfma_f32_16x16x32_bf16 v[130:133], v[50:53], v[170:173], 0
	v_mfma_f32_16x16x32_bf16 v[122:125], v[158:161], v[170:173], 0
	v_mfma_f32_16x16x32_bf16 v[114:117], v[50:53], v[178:181], 0
	v_mfma_f32_16x16x32_bf16 v[106:109], v[158:161], v[178:181], 0
	v_mfma_f32_16x16x32_bf16 v[98:101], v[50:53], v[186:189], 0
	v_mfma_f32_16x16x32_bf16 v[90:93], v[158:161], v[186:189], 0
	v_mfma_f32_16x16x32_bf16 v[82:85], v[50:53], v[194:197], 0
	v_mfma_f32_16x16x32_bf16 v[74:77], v[158:161], v[194:197], 0
	v_mfma_f32_16x16x32_bf16 v[130:133], v[146:149], v[174:177], v[130:133]
	v_mfma_f32_16x16x32_bf16 v[122:125], v[166:169], v[174:177], v[122:125]
	v_mfma_f32_16x16x32_bf16 v[114:117], v[146:149], v[182:185], v[114:117]
	v_mfma_f32_16x16x32_bf16 v[106:109], v[166:169], v[182:185], v[106:109]
	v_mfma_f32_16x16x32_bf16 v[98:101], v[146:149], v[190:193], v[98:101]
	v_mfma_f32_16x16x32_bf16 v[90:93], v[166:169], v[190:193], v[90:93]
	v_mfma_f32_16x16x32_bf16 v[82:85], v[146:149], v[198:201], v[82:85]
	v_mfma_f32_16x16x32_bf16 v[74:77], v[166:169], v[198:201], v[74:77]
	s_setprio 0
	s_barrier
	v_or_b32_e32 v163, 0x14000, v155
	s_mov_b32 m0, s14
	v_add_u32_e32 v165, 0x14400, v155
	ds_read_b128 v[202:205], v163
	ds_read_b128 v[206:209], v165
	v_add_u32_e32 v163, 0x14800, v155
	v_lshl_add_u64 v[218:219], s[28:29], 0, v[0:1]
	v_add_u32_e32 v165, 0x14c00, v155
	ds_read_b128 v[210:213], v163
	ds_read_b128 v[214:217], v165
	global_load_lds_dwordx4 v[218:219], off
	v_lshl_add_u64 v[220:221], s[28:29], 0, v[138:139]
	s_mov_b32 m0, s15
	s_nop 0
	global_load_lds_dwordx4 v[220:221], off
	s_barrier
; #define PG8_STAGE(bufoff, gbase, voff) do { _Pragma("unroll") for (int _i = 0; _i < 2; ++_i) \
;     __builtin_amdgcn_global_load_lds((const unsigned*)((const char*)(gbase) + (voff)[_i]), (PG8_LAS unsigned*)(lds + (bufoff) + ldsw + _i * 8192), 16, 0, 0); } while (0)
; #define PG8_LDA(dst, b, h) do { _Pragma("unroll") for (int m = 0; m < 4; ++m) _Pragma("unroll") for (int k = 0; k < 2; ++k) dst[m][k] = *(const PG8_LAS bf16x8*)(lds + PG8_SA(b, h) + aoff + m * 2048 + k * 1024); } while (0)
; #define PG8_LDB(dst, b, h) do { _Pragma("unroll") for (int n = 0; n < 2; ++n) _Pragma("unroll") for (int k = 0; k < 2; ++k) dst[n][k] = *(const PG8_LAS bf16x8*)(lds + PG8_SB(b, h) + boff + n * 2048 + k * 1024); } while (0)
; #define PG8_MMA(ai, bj, At, Bt) do { __builtin_amdgcn_s_setprio(1); _Pragma("unroll") for (int m = 0; m < 4; ++m) _Pragma("unroll") for (int n = 0; n < 2; ++n) _Pragma("unroll") for (int k = 0; k < 2; ++k) \
;     acc[ai][bj][m][n] = __builtin_amdgcn_mfma_f32_16x16x32_bf16(Bt[n][k], At[m][k], acc[ai][bj][m][n], 0, 0, 0); __builtin_amdgcn_s_setprio(0); } while (0)
; #define PG8_WAIT_V(n) asm volatile("s_waitcnt vmcnt(" #n ")" ::: "memory")
; #define PG8_WAIT_L(n) asm volatile("s_waitcnt lgkmcnt(" #n ")" ::: "memory")
; #define PG8_BAR __builtin_amdgcn_s_barrier()
; #define PG8_SCHED __builtin_amdgcn_sched_barrier(0)
; template <class Epi>
; DI void gemm_phase(const bf16_t* __restrict__ gA, const bf16_t* __restrict__ gBt, int M, int N, int K, const Epi& E, char* lds_generic) {
;     ...
;       PG8_WAIT_L(8); PG8_BAR; PG8_WAIT_L(0); PG8_MMA(0, 0, At, B0); PG8_BAR; PG8_SCHED;
;       PG8_LDB(B1, 0, 1); PG8_STAGE(PG8_SB(0, 0), b2, voffB);
;       PG8_BAR; PG8_WAIT_L(0); PG8_MMA(0, 1, At, B1); PG8_BAR;
;       PG8_LDA(At, 0, 1); PG8_STAGE(PG8_SA(0, 0), a2, voffA);
;       PG8_BAR; PG8_WAIT_L(0); PG8_MMA(1, 0, At, B0); PG8_BAR; PG8_SCHED;
;       PG8_STAGE(PG8_SB(0, 1), b2 + hstep, voffB);
;       PG8_WAIT_V(6); PG8_BAR; PG8_MMA(1, 1, At, B1); PG8_BAR;
	s_waitcnt lgkmcnt(0)
	s_setprio 1
	s_waitcnt lgkmcnt(0)
	v_mfma_f32_16x16x32_bf16 v[126:129], v[202:205], v[170:173], 0
	v_mfma_f32_16x16x32_bf16 v[118:121], v[210:213], v[170:173], 0
	v_mfma_f32_16x16x32_bf16 v[110:113], v[202:205], v[178:181], 0
	v_mfma_f32_16x16x32_bf16 v[102:105], v[210:213], v[178:181], 0
	v_mfma_f32_16x16x32_bf16 v[94:97], v[202:205], v[186:189], 0
	v_mfma_f32_16x16x32_bf16 v[86:89], v[210:213], v[186:189], 0
	v_mfma_f32_16x16x32_bf16 v[78:81], v[202:205], v[194:197], 0
	v_mfma_f32_16x16x32_bf16 v[70:73], v[210:213], v[194:197], 0
	v_mfma_f32_16x16x32_bf16 v[126:129], v[206:209], v[174:177], v[126:129]
	v_mfma_f32_16x16x32_bf16 v[118:121], v[214:217], v[174:177], v[118:121]
	v_mfma_f32_16x16x32_bf16 v[110:113], v[206:209], v[182:185], v[110:113]
	v_mfma_f32_16x16x32_bf16 v[102:105], v[214:217], v[182:185], v[102:105]
	v_mfma_f32_16x16x32_bf16 v[94:97], v[206:209], v[190:193], v[94:97]
	v_mfma_f32_16x16x32_bf16 v[86:89], v[214:217], v[190:193], v[86:89]
	v_mfma_f32_16x16x32_bf16 v[78:81], v[206:209], v[198:201], v[78:81]
	v_mfma_f32_16x16x32_bf16 v[70:73], v[214:217], v[198:201], v[70:73]
	s_setprio 0
	s_mov_b32 m0, s72
	v_lshl_add_u64 v[226:227], s[30:31], 0, v[134:135]
	s_barrier
	ds_read_b128 v[170:173], v154 offset:16384
	ds_read_b128 v[174:177], v154 offset:17408
	ds_read_b128 v[178:181], v154 offset:18432
	ds_read_b128 v[182:185], v154 offset:19456
	ds_read_b128 v[186:189], v154 offset:20480
	ds_read_b128 v[190:193], v154 offset:21504
	ds_read_b128 v[194:197], v154 offset:22528
	ds_read_b128 v[198:201], v154 offset:23552
	global_load_lds_dwordx4 v[226:227], off
	v_lshl_add_u64 v[228:229], s[30:31], 0, v[136:137]
	s_mov_b32 m0, s58
	s_nop 0
	global_load_lds_dwordx4 v[228:229], off
	s_barrier
	s_waitcnt lgkmcnt(0)
	s_setprio 1
	s_waitcnt lgkmcnt(0)
	v_mfma_f32_16x16x32_bf16 v[66:69], v[50:53], v[170:173], 0
	v_mfma_f32_16x16x32_bf16 v[58:61], v[158:161], v[170:173], 0
	v_mfma_f32_16x16x32_bf16 v[46:49], v[50:53], v[178:181], 0
	v_mfma_f32_16x16x32_bf16 v[38:41], v[158:161], v[178:181], 0
	v_mfma_f32_16x16x32_bf16 v[30:33], v[50:53], v[186:189], 0
	v_mfma_f32_16x16x32_bf16 v[22:25], v[158:161], v[186:189], 0
	v_mfma_f32_16x16x32_bf16 v[14:17], v[50:53], v[194:197], 0
	v_mfma_f32_16x16x32_bf16 v[6:9], v[158:161], v[194:197], 0
	v_mfma_f32_16x16x32_bf16 v[66:69], v[146:149], v[174:177], v[66:69]
	v_mfma_f32_16x16x32_bf16 v[58:61], v[166:169], v[174:177], v[58:61]
	v_mfma_f32_16x16x32_bf16 v[46:49], v[146:149], v[182:185], v[46:49]
	v_mfma_f32_16x16x32_bf16 v[38:41], v[166:169], v[182:185], v[38:41]
	v_mfma_f32_16x16x32_bf16 v[30:33], v[146:149], v[190:193], v[30:33]
	v_mfma_f32_16x16x32_bf16 v[22:25], v[166:169], v[190:193], v[22:25]
	v_mfma_f32_16x16x32_bf16 v[14:17], v[146:149], v[198:201], v[14:17]
	v_mfma_f32_16x16x32_bf16 v[6:9], v[166:169], v[198:201], v[6:9]
	s_setprio 0
	s_barrier
	s_add_u32 s24, s28, 0x40000
	s_addc_u32 s25, s29, 0
	s_mov_b32 m0, s59
	v_lshl_add_u64 v[50:51], s[24:25], 0, v[0:1]
	global_load_lds_dwordx4 v[50:51], off
	v_lshl_add_u64 v[50:51], s[24:25], 0, v[138:139]
	s_mov_b32 m0, s62
	s_nop 0
	global_load_lds_dwordx4 v[50:51], off
	s_waitcnt vmcnt(6)
	s_barrier
	s_setprio 1
	v_mfma_f32_16x16x32_bf16 v[54:57], v[210:213], v[170:173], 0
	v_mfma_f32_16x16x32_bf16 v[42:45], v[202:205], v[178:181], 0
	v_mfma_f32_16x16x32_bf16 v[34:37], v[210:213], v[178:181], 0
	v_mfma_f32_16x16x32_bf16 v[26:29], v[202:205], v[186:189], 0
	v_mfma_f32_16x16x32_bf16 v[18:21], v[210:213], v[186:189], 0
	v_mfma_f32_16x16x32_bf16 v[10:13], v[202:205], v[194:197], 0
	v_mfma_f32_16x16x32_bf16 v[2:5], v[210:213], v[194:197], 0
	v_mfma_f32_16x16x32_bf16 v[50:53], v[202:205], v[170:173], 0
	v_mfma_f32_16x16x32_bf16 v[54:57], v[214:217], v[174:177], v[54:57]
	v_mfma_f32_16x16x32_bf16 v[42:45], v[206:209], v[182:185], v[42:45]
	v_mfma_f32_16x16x32_bf16 v[34:37], v[214:217], v[182:185], v[34:37]
	v_mfma_f32_16x16x32_bf16 v[26:29], v[206:209], v[190:193], v[26:29]
	v_mfma_f32_16x16x32_bf16 v[18:21], v[214:217], v[190:193], v[18:21]
	v_mfma_f32_16x16x32_bf16 v[10:13], v[206:209], v[198:201], v[10:13]
	v_mfma_f32_16x16x32_bf16 v[2:5], v[214:217], v[198:201], v[2:5]
	v_mfma_f32_16x16x32_bf16 v[50:53], v[206:209], v[174:177], v[50:53]
	s_setprio 0
	v_or_b32_e32 v62, 0x18000, v155
	v_add_u32_e32 v146, 0x18400, v155
	v_add_u32_e32 v158, 0x18800, v155
	s_barrier
	s_branch .Lup605_p5

; #define PG8_STAGE(bufoff, gbase, voff) do { _Pragma("unroll") for (int _i = 0; _i < 2; ++_i) \
;     __builtin_amdgcn_global_load_lds((const unsigned*)((const char*)(gbase) + (voff)[_i]), (PG8_LAS unsigned*)(lds + (bufoff) + ldsw + _i * 8192), 16, 0, 0); } while (0)
; #define PG8_LDA(dst, b, h) do { _Pragma("unroll") for (int m = 0; m < 4; ++m) _Pragma("unroll") for (int k = 0; k < 2; ++k) dst[m][k] = *(const PG8_LAS bf16x8*)(lds + PG8_SA(b, h) + aoff + m * 2048 + k * 1024); } while (0)
; #define PG8_LDB(dst, b, h) do { _Pragma("unroll") for (int n = 0; n < 2; ++n) _Pragma("unroll") for (int k = 0; k < 2; ++k) dst[n][k] = *(const PG8_LAS bf16x8*)(lds + PG8_SB(b, h) + boff + n * 2048 + k * 1024); } while (0)
; #define PG8_MMA(ai, bj, At, Bt) do { __builtin_amdgcn_s_setprio(1); _Pragma("unroll") for (int m = 0; m < 4; ++m) _Pragma("unroll") for (int n = 0; n < 2; ++n) _Pragma("unroll") for (int k = 0; k < 2; ++k) \
;     acc[ai][bj][m][n] = __builtin_amdgcn_mfma_f32_16x16x32_bf16(Bt[n][k], At[m][k], acc[ai][bj][m][n], 0, 0, 0); __builtin_amdgcn_s_setprio(0); } while (0)
; #define PG8_WAIT_L(n) asm volatile("s_waitcnt lgkmcnt(" #n ")" ::: "memory")
; #define PG8_BAR __builtin_amdgcn_s_barrier()
; #define PG8_SCHED __builtin_amdgcn_sched_barrier(0)
; template <class Epi>
; DI void gemm_phase(const bf16_t* __restrict__ gA, const bf16_t* __restrict__ gBt, int M, int N, int K, const Epi& E, char* lds_generic) {
;     ...
;       PG8_LDB(B0, 1, 0); PG8_SCHED; PG8_LDA(At, 1, 0); PG8_STAGE(PG8_SA(0, 1), a2 + hstep, voffA);
;       PG8_WAIT_L(8); PG8_BAR; PG8_WAIT_L(0); PG8_MMA(0, 0, At, B0); PG8_BAR; PG8_SCHED;
;       PG8_LDB(B1, 1, 1); PG8_STAGE(PG8_SB(1, 0), b3, voffB);
;       PG8_BAR; PG8_WAIT_L(0); PG8_MMA(0, 1, At, B1); PG8_BAR;
.Lup605_p5:
	ds_read_b128 v[62:65], v62
	ds_read_b128 v[146:149], v146
	v_add_u32_e32 v163, 0x18c00, v155
	ds_read_b128 v[158:161], v158
	ds_read_b128 v[166:169], v163
	s_add_u32 s24, s30, 0x40000
	s_addc_u32 s25, s31, 0
	s_mov_b32 m0, s7
	v_lshl_add_u64 v[202:203], s[24:25], 0, v[134:135]
	ds_read_b128 v[170:173], v154 offset:32768
	ds_read_b128 v[174:177], v154 offset:33792
	ds_read_b128 v[178:181], v154 offset:34816
	ds_read_b128 v[182:185], v154 offset:35840
	ds_read_b128 v[186:189], v154 offset:36864
	ds_read_b128 v[190:193], v154 offset:37888
	ds_read_b128 v[194:197], v154 offset:38912
	ds_read_b128 v[198:201], v154 offset:39936
	global_load_lds_dwordx4 v[202:203], off
	v_lshl_add_u64 v[202:203], s[24:25], 0, v[136:137]
	s_mov_b32 m0, s12
	s_nop 0
	global_load_lds_dwordx4 v[202:203], off
	s_waitcnt lgkmcnt(8)
	s_barrier
	s_waitcnt lgkmcnt(0)
	s_setprio 1
	s_waitcnt lgkmcnt(0)
	v_mfma_f32_16x16x32_bf16 v[130:133], v[62:65], v[170:173], v[130:133]
	v_mfma_f32_16x16x32_bf16 v[122:125], v[158:161], v[170:173], v[122:125]
	v_mfma_f32_16x16x32_bf16 v[114:117], v[62:65], v[178:181], v[114:117]
	v_mfma_f32_16x16x32_bf16 v[106:109], v[158:161], v[178:181], v[106:109]
	v_mfma_f32_16x16x32_bf16 v[98:101], v[62:65], v[186:189], v[98:101]
	v_mfma_f32_16x16x32_bf16 v[90:93], v[158:161], v[186:189], v[90:93]
	v_mfma_f32_16x16x32_bf16 v[82:85], v[62:65], v[194:197], v[82:85]
	v_mfma_f32_16x16x32_bf16 v[74:77], v[158:161], v[194:197], v[74:77]
	v_mfma_f32_16x16x32_bf16 v[130:133], v[146:149], v[174:177], v[130:133]
	v_mfma_f32_16x16x32_bf16 v[122:125], v[166:169], v[174:177], v[122:125]
	v_mfma_f32_16x16x32_bf16 v[114:117], v[146:149], v[182:185], v[114:117]
	v_mfma_f32_16x16x32_bf16 v[106:109], v[166:169], v[182:185], v[106:109]
	v_mfma_f32_16x16x32_bf16 v[98:101], v[146:149], v[190:193], v[98:101]
	v_mfma_f32_16x16x32_bf16 v[90:93], v[166:169], v[190:193], v[90:93]
	v_mfma_f32_16x16x32_bf16 v[82:85], v[146:149], v[198:201], v[82:85]
	v_mfma_f32_16x16x32_bf16 v[74:77], v[166:169], v[198:201], v[74:77]
	s_setprio 0
	s_barrier
	v_or_b32_e32 v163, 0x1c000, v155
	s_mov_b32 m0, s13
	v_add_u32_e32 v165, 0x1c400, v155
	ds_read_b128 v[202:205], v163
	ds_read_b128 v[206:209], v165
	v_add_u32_e32 v163, 0x1c800, v155
	v_lshl_add_u64 v[218:219], v[218:219], 0, s[10:11]
	v_add_u32_e32 v165, 0x1cc00, v155
	ds_read_b128 v[210:213], v163
	ds_read_b128 v[214:217], v165
	global_load_lds_dwordx4 v[218:219], off
	v_lshl_add_u64 v[218:219], v[220:221], 0, s[10:11]
	s_mov_b32 m0, s35
	s_nop 0
	global_load_lds_dwordx4 v[218:219], off
	s_barrier
	s_waitcnt lgkmcnt(0)
	s_setprio 1
	s_waitcnt lgkmcnt(0)
	v_mfma_f32_16x16x32_bf16 v[126:129], v[202:205], v[170:173], v[126:129]
	v_mfma_f32_16x16x32_bf16 v[118:121], v[210:213], v[170:173], v[118:121]
	v_mfma_f32_16x16x32_bf16 v[110:113], v[202:205], v[178:181], v[110:113]
	v_mfma_f32_16x16x32_bf16 v[102:105], v[210:213], v[178:181], v[102:105]
	v_mfma_f32_16x16x32_bf16 v[94:97], v[202:205], v[186:189], v[94:97]
	v_mfma_f32_16x16x32_bf16 v[86:89], v[210:213], v[186:189], v[86:89]
	v_mfma_f32_16x16x32_bf16 v[78:81], v[202:205], v[194:197], v[78:81]
	v_mfma_f32_16x16x32_bf16 v[70:73], v[210:213], v[194:197], v[70:73]
	v_mfma_f32_16x16x32_bf16 v[126:129], v[206:209], v[174:177], v[126:129]
	v_mfma_f32_16x16x32_bf16 v[118:121], v[214:217], v[174:177], v[118:121]
	v_mfma_f32_16x16x32_bf16 v[110:113], v[206:209], v[182:185], v[110:113]
	v_mfma_f32_16x16x32_bf16 v[102:105], v[214:217], v[182:185], v[102:105]
	v_mfma_f32_16x16x32_bf16 v[94:97], v[206:209], v[190:193], v[94:97]
	v_mfma_f32_16x16x32_bf16 v[86:89], v[214:217], v[190:193], v[86:89]
	v_mfma_f32_16x16x32_bf16 v[78:81], v[206:209], v[198:201], v[78:81]
	v_mfma_f32_16x16x32_bf16 v[70:73], v[214:217], v[198:201], v[70:73]
	s_setprio 0
	s_mov_b32 m0, s53
	v_lshl_add_u64 v[218:219], v[226:227], 0, s[10:11]
	s_barrier
; #define PG8_STAGE(bufoff, gbase, voff) do { _Pragma("unroll") for (int _i = 0; _i < 2; ++_i) \
;     __builtin_amdgcn_global_load_lds((const unsigned*)((const char*)(gbase) + (voff)[_i]), (PG8_LAS unsigned*)(lds + (bufoff) + ldsw + _i * 8192), 16, 0, 0); } while (0)
; #define PG8_LDA(dst, b, h) do { _Pragma("unroll") for (int m = 0; m < 4; ++m) _Pragma("unroll") for (int k = 0; k < 2; ++k) dst[m][k] = *(const PG8_LAS bf16x8*)(lds + PG8_SA(b, h) + aoff + m * 2048 + k * 1024); } while (0)
; #define PG8_MMA(ai, bj, At, Bt) do { __builtin_amdgcn_s_setprio(1); _Pragma("unroll") for (int m = 0; m < 4; ++m) _Pragma("unroll") for (int n = 0; n < 2; ++n) _Pragma("unroll") for (int k = 0; k < 2; ++k) \
;     acc[ai][bj][m][n] = __builtin_amdgcn_mfma_f32_16x16x32_bf16(Bt[n][k], At[m][k], acc[ai][bj][m][n], 0, 0, 0); __builtin_amdgcn_s_setprio(0); } while (0)
; #define PG8_WAIT_V(n) asm volatile("s_waitcnt vmcnt(" #n ")" ::: "memory")
; #define PG8_WAIT_L(n) asm volatile("s_waitcnt lgkmcnt(" #n ")" ::: "memory")
; #define PG8_BAR __builtin_amdgcn_s_barrier()
; #define PG8_SCHED __builtin_amdgcn_sched_barrier(0)
; #define PG8_RTAB_LOAD(var, unit) do { if constexpr (Epi::NEEDS_R) { var = *(const uint4*)(E.ssq + (size_t)((unit).pm * BM + (tid >> 1)) * 16 + (tid & 1) * 8); } } while (0)
; template <class Epi>
; DI void gemm_phase(const bf16_t* __restrict__ gA, const bf16_t* __restrict__ gBt, int M, int N, int K, const Epi& E, char* lds_generic) {
;     ...
;       PG8_LDA(At, 1, 1); PG8_STAGE(PG8_SA(1, 0), a3, voffA);
;       PG8_BAR; PG8_WAIT_L(0); PG8_MMA(1, 0, At, B0); PG8_BAR; PG8_SCHED;
;       PG8_STAGE(PG8_SB(1, 1), b3 + hstep, voffB);
;       PG8_WAIT_V(6); PG8_BAR; PG8_MMA(1, 1, At, B1); PG8_BAR;
;     }
;     uint4 rtn_ = {0u, 0u, 0u, 0u};
;     if (has_next) PG8_RTAB_LOAD(rtn_, nxt);
	ds_read_b128 v[170:173], v154 offset:49152
	ds_read_b128 v[174:177], v154 offset:50176
	ds_read_b128 v[178:181], v154 offset:51200
	ds_read_b128 v[182:185], v154 offset:52224
	ds_read_b128 v[186:189], v154 offset:53248
	ds_read_b128 v[190:193], v154 offset:54272
	ds_read_b128 v[194:197], v154 offset:55296
	ds_read_b128 v[198:201], v154 offset:56320
	global_load_lds_dwordx4 v[218:219], off
	v_lshl_add_u64 v[218:219], v[228:229], 0, s[10:11]
	s_mov_b32 m0, s74
	s_nop 0
	global_load_lds_dwordx4 v[218:219], off
	s_barrier
	s_waitcnt lgkmcnt(0)
	s_setprio 1
	s_waitcnt lgkmcnt(0)
	v_mfma_f32_16x16x32_bf16 v[66:69], v[62:65], v[170:173], v[66:69]
	v_mfma_f32_16x16x32_bf16 v[58:61], v[158:161], v[170:173], v[58:61]
	v_mfma_f32_16x16x32_bf16 v[46:49], v[62:65], v[178:181], v[46:49]
	v_mfma_f32_16x16x32_bf16 v[38:41], v[158:161], v[178:181], v[38:41]
	v_mfma_f32_16x16x32_bf16 v[30:33], v[62:65], v[186:189], v[30:33]
	v_mfma_f32_16x16x32_bf16 v[22:25], v[158:161], v[186:189], v[22:25]
	v_mfma_f32_16x16x32_bf16 v[14:17], v[62:65], v[194:197], v[14:17]
	v_mfma_f32_16x16x32_bf16 v[6:9], v[158:161], v[194:197], v[6:9]
	v_mfma_f32_16x16x32_bf16 v[66:69], v[146:149], v[174:177], v[66:69]
	v_mfma_f32_16x16x32_bf16 v[58:61], v[166:169], v[174:177], v[58:61]
	v_mfma_f32_16x16x32_bf16 v[46:49], v[146:149], v[182:185], v[46:49]
	v_mfma_f32_16x16x32_bf16 v[38:41], v[166:169], v[182:185], v[38:41]
	v_mfma_f32_16x16x32_bf16 v[30:33], v[146:149], v[190:193], v[30:33]
	v_mfma_f32_16x16x32_bf16 v[22:25], v[166:169], v[190:193], v[22:25]
	v_mfma_f32_16x16x32_bf16 v[14:17], v[146:149], v[198:201], v[14:17]
	v_mfma_f32_16x16x32_bf16 v[6:9], v[166:169], v[198:201], v[6:9]
	s_setprio 0
	s_barrier
	s_add_u32 s24, s28, 0x40080
	s_addc_u32 s25, s29, 0
	s_mov_b32 m0, s60
	v_lshl_add_u64 v[62:63], s[24:25], 0, v[0:1]
	global_load_lds_dwordx4 v[62:63], off
	v_lshl_add_u64 v[62:63], s[24:25], 0, v[138:139]
	s_mov_b32 m0, s6
	s_nop 0
	global_load_lds_dwordx4 v[62:63], off
	s_waitcnt vmcnt(6)
	s_barrier
	s_setprio 1
	v_mfma_f32_16x16x32_bf16 v[50:53], v[202:205], v[170:173], v[50:53]
	v_mfma_f32_16x16x32_bf16 v[62:65], v[206:209], v[174:177], v[50:53]
	v_mfma_f32_16x16x32_bf16 v[50:53], v[210:213], v[170:173], v[54:57]
	v_mfma_f32_16x16x32_bf16 v[42:45], v[202:205], v[178:181], v[42:45]
	v_mfma_f32_16x16x32_bf16 v[34:37], v[210:213], v[178:181], v[34:37]
	v_mfma_f32_16x16x32_bf16 v[26:29], v[202:205], v[186:189], v[26:29]
	v_mfma_f32_16x16x32_bf16 v[18:21], v[210:213], v[186:189], v[18:21]
	v_mfma_f32_16x16x32_bf16 v[10:13], v[202:205], v[194:197], v[10:13]
	v_mfma_f32_16x16x32_bf16 v[2:5], v[210:213], v[194:197], v[2:5]
	v_mfma_f32_16x16x32_bf16 v[54:57], v[214:217], v[174:177], v[50:53]
	v_mfma_f32_16x16x32_bf16 v[42:45], v[206:209], v[182:185], v[42:45]
	v_mfma_f32_16x16x32_bf16 v[34:37], v[214:217], v[182:185], v[34:37]
	v_mfma_f32_16x16x32_bf16 v[26:29], v[206:209], v[190:193], v[26:29]
	v_mfma_f32_16x16x32_bf16 v[18:21], v[214:217], v[190:193], v[18:21]
	v_mfma_f32_16x16x32_bf16 v[10:13], v[206:209], v[198:201], v[10:13]
	v_mfma_f32_16x16x32_bf16 v[2:5], v[214:217], v[198:201], v[2:5]
	s_setprio 0
	s_add_i32 s23, s23, 2
	s_add_u32 vcc_lo, vcc_lo, 0x100
	s_addc_u32 vcc_hi, vcc_hi, 0
	s_add_u32 s87, s87, 0x100
	s_addc_u32 s22, s22, 0
	s_cmp_gt_u32 s23, 13
	s_barrier
	s_cbranch_scc0 .LBB0_605
	v_mov_b32_e32 v50, 0
	s_and_b64 vcc, exec, s[38:39]
	v_mov_b32_e32 v51, 0
	v_mov_b32_e32 v52, 0
	v_mov_b32_e32 v53, 0
	s_cbranch_vccz .LBB0_608
	v_lshl_add_u32 v50, s86, 8, v150
	v_ashrrev_i32_e32 v51, 31, v50
	v_lshlrev_b64 v[50:51], 5, v[50:51]
	v_lshl_add_u64 v[50:51], v[140:141], 0, v[50:51]
	global_load_dwordx4 v[50:53], v[50:51], off
